# P0 weight transpose: items decoded so the 8 waves of a workgroup write the 8 pieces of each 128-byte output line; MLA prefetch setup in MFMA shadow
# speedup vs baseline: 1.0781x; 1.0061x over previous
.LBB0_34:
	s_lshr_b32 s14, s52, 3
	s_mul_i32 s53, s4, s14
	s_mul_hi_u32 s14, s33, s23
	s_mul_i32 s14, s14, s22
	s_sub_i32 s14, s33, s14
	s_sub_i32 s15, s14, s22
	s_cmp_ge_u32 s14, s22
	s_cselect_b32 s14, s15, s14
	s_sub_i32 s15, s14, s22
	s_cmp_ge_u32 s14, s22
	s_cselect_b32 s14, s15, s14
	v_subrev_u32_e32 v3, s14, v42
	v_sub_u32_e32 v4, 0, v3
	v_ashrrev_i32_e32 v2, 31, v3
	v_max_i32_e32 v3, v3, v4
	v_mul_hi_u32 v4, v3, s23
	v_mul_lo_u32 v4, v4, s22
	v_sub_u32_e32 v3, v3, v4
	v_subrev_u32_e32 v4, s22, v3
	v_cmp_le_u32_e32 vcc, s22, v3
	s_nop 1
	v_cndmask_b32_e32 v3, v3, v4, vcc
	v_subrev_u32_e32 v4, s22, v3
	v_cmp_le_u32_e32 vcc, s22, v3
	s_nop 1
	v_cndmask_b32_e32 v3, v3, v4, vcc
	v_xor_b32_e32 v3, v3, v2
	v_sub_u32_e32 v44, v3, v2
	v_cmp_gt_i32_e32 vcc, s53, v44
	s_and_saveexec_b64 s[14:15], vcc
	s_cbranch_execz .LBB0_6
	s_lshr_b32 s96, s52, 3
	v_cvt_f32_u32_e32 v4, s96
	s_cmp_lg_u64 s[12:13], 0
	v_lshl_or_b32 v3, v3, 8, v34
	v_lshlrev_b32_e32 v2, 8, v2
	v_rcp_iflag_f32_e32 v4, v4
	s_cselect_b64 s[18:19], -1, 0
	s_sub_i32 s20, 0, s96
	v_sub_u32_e32 v36, v3, v2
	v_mul_f32_e32 v4, 0x4f7ffffe, v4
	v_cvt_u32_f32_e32 v4, v4
	s_lshl_b32 s21, s4, 8
	s_mov_b64 s[16:17], 0
	s_sub_i32 s54, 0, s21
	v_mul_lo_u32 v2, s20, v4
	v_mul_hi_u32 v2, v4, v2
	v_add_u32_e32 v45, v4, v2
	s_branch .LBB0_37

.LBB0_37:
	v_sub_u32_e32 v3, 0, v44
	v_max_i32_e32 v3, v44, v3
	v_mul_hi_u32 v4, v3, v45
	v_mul_lo_u32 v5, v4, s96
	v_sub_u32_e32 v3, v3, v5
	v_add_u32_e32 v5, 1, v4
	v_cmp_le_u32_e32 vcc, s96, v3
	v_ashrrev_i32_e32 v2, 31, v44
	s_nop 0
	v_cndmask_b32_e32 v4, v4, v5, vcc
	v_subrev_u32_e32 v5, s96, v3
	v_cndmask_b32_e32 v3, v3, v5, vcc
	v_add_u32_e32 v5, 1, v4
	v_cmp_le_u32_e32 vcc, s96, v3
	s_nop 1
	v_cndmask_b32_e32 v3, v4, v5, vcc
	v_xor_b32_e32 v3, v3, v2
	v_sub_u32_e32 v2, v3, v2
	v_lshl_add_u32 v38, v2, 8, v34
	v_mul_lo_u32 v40, v2, s96
	v_sub_u32_e32 v40, v44, v40
	v_lshlrev_b32_e32 v40, 3, v40
	v_cmp_le_i32_e32 vcc, s35, v38
	v_ashrrev_i32_e32 v41, 31, v40
	s_and_saveexec_b64 s[20:21], vcc
	s_xor_b64 s[20:21], exec, s[20:21]
	v_mov_b32_e32 v39, v43
	s_or_saveexec_b64 s[20:21], s[20:21]
	v_mov_b32_e32 v18, 0
	v_mov_b32_e32 v19, 0
	v_mov_b32_e32 v20, 0
	v_mov_b32_e32 v21, 0
	v_mov_b32_e32 v2, 0
	v_mov_b32_e32 v3, 0
	v_mov_b32_e32 v4, 0
	v_mov_b32_e32 v5, 0
	v_mov_b32_e32 v6, 0
	v_mov_b32_e32 v7, 0
	v_mov_b32_e32 v8, 0
	v_mov_b32_e32 v9, 0
	v_mov_b32_e32 v10, 0
	v_mov_b32_e32 v11, 0
	v_mov_b32_e32 v12, 0
	v_mov_b32_e32 v13, 0
	v_mov_b32_e32 v14, 0
	v_mov_b32_e32 v15, 0
	v_mov_b32_e32 v16, 0
	v_mov_b32_e32 v17, 0
	v_mov_b32_e32 v22, 0
	v_mov_b32_e32 v23, 0
	v_mov_b32_e32 v24, 0
	v_mov_b32_e32 v25, 0
	v_mov_b32_e32 v26, 0
	v_mov_b32_e32 v27, 0
	v_mov_b32_e32 v28, 0
	v_mov_b32_e32 v29, 0
	v_mov_b32_e32 v30, 0
	v_mov_b32_e32 v31, 0
	v_mov_b32_e32 v32, 0
	v_mov_b32_e32 v33, 0
	s_xor_b64 exec, exec, s[20:21]
	s_cbranch_execz .LBB0_36
	v_or_b32_e32 v4, 1, v40
	v_or_b32_e32 v10, 2, v40
	v_or_b32_e32 v12, 3, v40
	v_or_b32_e32 v20, 4, v40
	v_or_b32_e32 v22, 5, v40
	v_ashrrev_i32_e32 v39, 31, v38
	v_mul_lo_u32 v32, v41, s35
	v_mad_u64_u32 v[2:3], s[56:57], v40, s35, 0
	v_mad_u64_u32 v[4:5], s[56:57], v4, s35, 0
	v_mad_u64_u32 v[10:11], s[56:57], v10, s35, 0
	v_mad_u64_u32 v[12:13], s[56:57], v12, s35, 0
	v_mad_u64_u32 v[20:21], s[56:57], v20, s35, 0
	v_mad_u64_u32 v[22:23], s[56:57], v22, s35, 0
	v_lshl_add_u64 v[18:19], v[38:39], 2, s[6:7]
	v_add_u32_e32 v3, v3, v32
	v_add_u32_e32 v5, v5, v32
	v_add_u32_e32 v11, v11, v32
	v_add_u32_e32 v13, v13, v32
	v_add_u32_e32 v21, v21, v32
	v_add_u32_e32 v23, v23, v32
	v_lshl_add_u64 v[2:3], v[2:3], 2, v[18:19]
	v_lshl_add_u64 v[6:7], v[4:5], 2, v[18:19]
	v_lshl_add_u64 v[10:11], v[10:11], 2, v[18:19]
	v_lshl_add_u64 v[14:15], v[12:13], 2, v[18:19]
	v_lshl_add_u64 v[20:21], v[20:21], 2, v[18:19]
	v_lshl_add_u64 v[26:27], v[22:23], 2, v[18:19]
	global_load_dwordx4 v[2:5], v[2:3], off nt
	s_nop 0
	global_load_dwordx4 v[6:9], v[6:7], off nt
	s_nop 0
	global_load_dwordx4 v[10:13], v[10:11], off nt
	s_nop 0
	global_load_dwordx4 v[14:17], v[14:15], off nt
	s_nop 0
	global_load_dwordx4 v[22:25], v[20:21], off nt
	s_nop 0
	global_load_dwordx4 v[26:29], v[26:27], off nt
	v_or_b32_e32 v20, 6, v40
	v_or_b32_e32 v30, 7, v40
	v_mad_u64_u32 v[20:21], s[56:57], v20, s35, 0
	v_mad_u64_u32 v[30:31], s[56:57], v30, s35, 0
	v_add_u32_e32 v21, v21, v32
	v_add_u32_e32 v31, v31, v32
	v_lshl_add_u64 v[20:21], v[20:21], 2, v[18:19]
	v_lshl_add_u64 v[18:19], v[30:31], 2, v[18:19]
	global_load_dwordx4 v[30:33], v[20:21], off nt
	s_nop 0
	global_load_dwordx4 v[18:21], v[18:19], off nt
	s_andn2_b64 vcc, exec, s[18:19]
	s_cbranch_vccnz .LBB0_36
	v_lshl_add_u64 v[50:51], v[40:41], 2, s[12:13]
	global_load_dwordx4 v[46:49], v[50:51], off
	s_nop 0
	global_load_dwordx4 v[50:53], v[50:51], off offset:16
	s_waitcnt vmcnt(1)
	v_pk_mul_f32 v[4:5], v[4:5], v[46:47] op_sel_hi:[1,0]
	v_pk_mul_f32 v[2:3], v[2:3], v[46:47] op_sel_hi:[1,0]
	v_pk_mul_f32 v[8:9], v[8:9], v[46:47] op_sel:[0,1]
	v_pk_mul_f32 v[6:7], v[6:7], v[46:47] op_sel:[0,1]
	v_pk_mul_f32 v[12:13], v[12:13], v[48:49] op_sel_hi:[1,0]
	v_pk_mul_f32 v[10:11], v[10:11], v[48:49] op_sel_hi:[1,0]
	v_mov_b32_e32 v46, v49
	s_waitcnt vmcnt(0)
	v_mov_b32_e32 v48, v53
	v_pk_mul_f32 v[24:25], v[24:25], v[50:51] op_sel_hi:[1,0]
	v_pk_mul_f32 v[22:23], v[22:23], v[50:51] op_sel_hi:[1,0]
	v_pk_mul_f32 v[28:29], v[28:29], v[50:51] op_sel:[0,1]
	v_pk_mul_f32 v[26:27], v[26:27], v[50:51] op_sel:[0,1]
	v_pk_mul_f32 v[32:33], v[32:33], v[52:53] op_sel_hi:[1,0]
	v_pk_mul_f32 v[30:31], v[30:31], v[52:53] op_sel_hi:[1,0]
	v_pk_mul_f32 v[16:17], v[16:17], v[46:47] op_sel_hi:[1,0]
	v_pk_mul_f32 v[14:15], v[14:15], v[46:47] op_sel_hi:[1,0]
	v_pk_mul_f32 v[20:21], v[20:21], v[48:49] op_sel_hi:[1,0]
	v_pk_mul_f32 v[18:19], v[18:19], v[48:49] op_sel_hi:[1,0]
	s_branch .LBB0_36

.Lmla_fast_havek:
	s_mov_b32 s42, 0
	s_andn2_b64 vcc, exec, s[38:39]
	s_cbranch_vccnz .Lmla_fast_nodma
	s_add_i32 s34, s30, 2
	s_cmp_gt_u32 s34, s14
	s_cbranch_scc1 .Lmla_fast_d2
	s_and_b32 s8, s34, 2
	s_mulk_i32 s8, 0x6400
	s_add_i32 s34, s8, 0
	s_add_i32 s8, s34, s5
	s_mov_b32 m0, s8
	s_and_b64 vcc, exec, s[36:37]
	global_load_lds_dwordx4 v66, s[26:27]
	s_add_i32 m0, s8, 0x2000
	v_add_u32_e32 v66, v66, v134
	global_load_lds_dwordx4 v68, s[26:27]
	s_add_i32 m0, s8, 0x4000
	v_add_u32_e32 v68, v68, v136
	global_load_lds_dwordx4 v70, s[26:27]
	v_add_u32_e32 v70, v70, v138
	s_cbranch_vccnz .Lmla_fast_d2
	s_add_i32 m0, s34, 0x6000
	s_nop 0
	global_load_lds_dwordx4 v72, s[26:27]
	v_add_u32_e32 v72, v72, v140
.Lmla_fast_d2:
	s_cmp_gt_u32 s30, s13
	s_cbranch_scc1 .Lmla_fast_nodma
	s_add_i32 s8, s30, -1
	s_and_b32 s8, s8, 3
	s_mulk_i32 s8, 0x6400
	s_add_i32 s34, s8, 0
	s_add_i32 s8, s34, s5
	s_mov_b32 m0, s8
	s_and_b64 vcc, exec, s[36:37]
	global_load_lds_dwordx4 v66, s[26:27]
	s_add_i32 m0, s8, 0x2000
	v_add_u32_e32 v66, v66, v134
	global_load_lds_dwordx4 v68, s[26:27]
	s_add_i32 m0, s8, 0x4000
	v_add_u32_e32 v68, v68, v136
	global_load_lds_dwordx4 v70, s[26:27]
	v_add_u32_e32 v70, v70, v138
	s_cbranch_vccnz .Lmla_fast_nodma
	s_add_i32 m0, s34, 0x6000
	s_nop 0
	global_load_lds_dwordx4 v72, s[26:27]
	v_add_u32_e32 v72, v72, v140

.Lmla_fast_ok:
	v_cvt_pk_bf16_f32 v166, v202, v203
	v_cvt_pk_bf16_f32 v167, v204, v205
	v_cvt_pk_bf16_f32 v168, v206, v207
	v_cvt_pk_bf16_f32 v169, v208, v209
	s_waitcnt lgkmcnt(0)
	s_nop 0
	v_mfma_f32_32x32x16_bf16 v[18:33], v[126:129], v[166:169], v[18:33]
	s_add_i32 s34, s31, 64
	s_cmp_le_u32 s34, s4
	s_cselect_b32 s42, 1, 0
	s_add_i32 s8, s30, 1
	s_and_b32 s8, s8, 3
	s_mulk_i32 s8, 0x6400
	v_add3_u32 v0, s8, v143, v132
	v_mfma_f32_32x32x16_bf16 v[2:17], v[122:125], v[166:169], v[2:17]
	v_cvt_pk_bf16_f32 v170, v210, v211
	v_cvt_pk_bf16_f32 v171, v212, v213
	v_cvt_pk_bf16_f32 v172, v214, v215
	v_cvt_pk_bf16_f32 v173, v216, v217
	v_exp_f32_e32 v218, v34
	v_exp_f32_e32 v219, v35
	v_mfma_f32_32x32x16_bf16 v[18:33], v[118:121], v[170:173], v[18:33]
	v_exp_f32_e32 v220, v36
	v_exp_f32_e32 v221, v37
	ds_read_b128 v[194:197], v0
	ds_read_b128 v[150:153], v0 offset:32
	v_mfma_f32_32x32x16_bf16 v[2:17], v[114:117], v[170:173], v[2:17]
	v_exp_f32_e32 v222, v38
	v_exp_f32_e32 v223, v39
	v_exp_f32_e32 v224, v40
	v_exp_f32_e32 v225, v41
	v_cvt_pk_bf16_f32 v166, v218, v219
	v_cvt_pk_bf16_f32 v167, v220, v221
	v_cvt_pk_bf16_f32 v168, v222, v223
	v_cvt_pk_bf16_f32 v169, v224, v225
	ds_read_b128 v[158:161], v0 offset:64
	ds_read_b128 v[162:165], v0 offset:96
	v_mfma_f32_32x32x16_bf16 v[18:33], v[110:113], v[166:169], v[18:33]
	v_exp_f32_e32 v226, v42
	v_exp_f32_e32 v227, v43
	v_exp_f32_e32 v228, v44
	v_mfma_f32_32x32x16_bf16 v[2:17], v[106:109], v[166:169], v[2:17]
	v_exp_f32_e32 v229, v45
	v_exp_f32_e32 v230, v46
	v_exp_f32_e32 v231, v47
	v_exp_f32_e32 v232, v48
	v_exp_f32_e32 v233, v49
	ds_read_b128 v[174:177], v0 offset:128
	ds_read_b128 v[178:181], v0 offset:160
	v_cvt_pk_bf16_f32 v170, v226, v227
	v_cvt_pk_bf16_f32 v171, v228, v229
	v_cvt_pk_bf16_f32 v172, v230, v231
	v_cvt_pk_bf16_f32 v173, v232, v233
	s_nop 1
	v_mfma_f32_32x32x16_bf16 v[18:33], v[102:105], v[170:173], v[18:33]
	v_mfma_f32_32x32x16_bf16 v[2:17], v[98:101], v[170:173], v[2:17]
	s_add_i32 s30, s30, 1
	s_add_i32 s31, s31, 64
	v_subrev_u32_e32 v146, 64, v146
	s_cmp_lg_u32 s42, 0
	s_cbranch_scc0 .Lmla_fast_generic
	s_not_b64 s[38:39], s[38:39]
	s_not_b64 s[16:17], s[38:39]
	s_branch .Lmla_fast
